# static priority raise for waves 0-3 (the other half) before each of the 20 GEMM K-loops, per-cluster flips deleted; otherwise v67
# speedup vs baseline: 1.0189x; 1.0071x over previous
; __device__ __forceinline__ int fresh_lane() { int l; asm volatile("v_mbcnt_lo_u32_b32 %0, -1, 0\n\tv_mbcnt_hi_u32_b32 %0, -1, %0" : "=v"(l)); return l; }
;     __device__ __forceinline__ void prefill(const Unit& u, int wr, int wc, int fr, int fq) const { float rs[2][4]; rows_rstd_c<false>(ssq, u.pm * BM + wr * 64 + fr, fr, fq, wr * 4 + wc, 0, tab, rs); }
;     __device__ __forceinline__ void prefill(const Unit& u, int wr, int wc, int fr, int fq) const { float rs[2][4]; rows_rstd_c<false>(ssq, u.pm * BM + wr * 64 + fr, fr, fq, wr * 4 + wc, 0, tab, rs); }
;     __device__ __forceinline__ void prefill(const Unit& u, int wr, int wc, int fr, int fq) const { float rs[2][4]; rows_rstd_c<false>(ssq, u.pm * BM + wr * 64 + fr, fr, fq, wr * 4 + wc, 0, tab, rs); }
; #define PG8_BAR __builtin_amdgcn_s_barrier()
; template <class Epi, class Sched, bool ALIGN_EPI = false, bool SP2 = false>
; __device__ __forceinline__ void gemm_phase(PG8_LAS unsigned char* lds, const Gemm g, const Sched& S, const Epi& E, const int wid  ) {
;     ...
; #pragma unroll
;         for (int a = 0; a < 2; ++a)
; #pragma unroll
;             for (int b = 0; b < 2; ++b)
; #pragma unroll
;                 for (int m = 0; m < 4; ++m)
; #pragma unroll
;                     for (int n = 0; n < 2; ++n) acc[a][b][m][n] = (f32x4){0.f, 0.f, 0.f, 0.f};
;         cur = nxt; cA = nA; cB = nB; ++ui;
;         if constexpr (Epi::PREFILL) { if (!cur.same) { const int l3 = fresh_lane(); E.prefill(cur, wr, wc, l3 & 15, l3 >> 4); cur.same = 1; } }
;         if constexpr (ALIGN_EPI) { if (wr == 1) PG8_BAR; }
.LBB0_203:
	s_lshl_b32 s60, s59, 20
	s_and_b64 s[14:15], s[4:5], exec
	s_cselect_b32 s63, s60, s65
	s_lshl_b32 s61, s58, 20
	s_and_b64 s[14:15], s[4:5], exec
	v_mov_b32_e32 v0, 0
	s_cselect_b32 s64, s61, s66
	s_add_i32 s65, s65, 0x80080
	s_addk_i32 s66, 0x100
	s_mov_b32 s67, -2
	v_mov_b32_e32 v1, v0
	s_waitcnt lgkmcnt(7)
	v_mov_b32_e32 v2, v0
	v_mov_b32_e32 v3, v0
	s_waitcnt lgkmcnt(6)
	v_mov_b32_e32 v4, v0
	v_mov_b32_e32 v5, v0
	s_waitcnt lgkmcnt(5)
	v_mov_b32_e32 v6, v0
	v_mov_b32_e32 v7, v0
	s_waitcnt lgkmcnt(2)
	v_mov_b32_e32 v12, v0
	v_mov_b32_e32 v13, v0
	s_waitcnt lgkmcnt(1)
	v_mov_b32_e32 v14, v0
	v_mov_b32_e32 v15, v0
	v_mov_b32_e32 v20, v0
	v_mov_b32_e32 v21, v0
	v_mov_b32_e32 v22, v0
	v_mov_b32_e32 v23, v0
	v_mov_b32_e32 v28, v0
	v_mov_b32_e32 v29, v0
	v_mov_b32_e32 v30, v0
	v_mov_b32_e32 v31, v0
	v_mov_b32_e32 v36, v0
	v_mov_b32_e32 v37, v0
	v_mov_b32_e32 v38, v0
	v_mov_b32_e32 v39, v0
	v_mov_b32_e32 v44, v0
	v_mov_b32_e32 v45, v0
	v_mov_b32_e32 v46, v0
	v_mov_b32_e32 v47, v0
	v_mov_b32_e32 v52, v0
	v_mov_b32_e32 v53, v0
	v_mov_b32_e32 v54, v0
	v_mov_b32_e32 v55, v0
	v_mov_b32_e32 v8, v0
	v_mov_b32_e32 v9, v0
	v_mov_b32_e32 v10, v0
	v_mov_b32_e32 v11, v0
	s_waitcnt lgkmcnt(0)
	v_mov_b32_e32 v16, v0
	v_mov_b32_e32 v17, v0
	s_waitcnt lgkmcnt(0)
	v_mov_b32_e32 v18, v0
	v_mov_b32_e32 v19, v0
	v_mov_b32_e32 v24, v0
	v_mov_b32_e32 v25, v0
	v_mov_b32_e32 v26, v0
	v_mov_b32_e32 v27, v0
	v_mov_b32_e32 v32, v0
	v_mov_b32_e32 v33, v0
	v_mov_b32_e32 v34, v0
	v_mov_b32_e32 v35, v0
	v_mov_b32_e32 v40, v0
	v_mov_b32_e32 v41, v0
	v_mov_b32_e32 v42, v0
	v_mov_b32_e32 v43, v0
	v_mov_b32_e32 v48, v0
	v_mov_b32_e32 v49, v0
	v_mov_b32_e32 v50, v0
	v_mov_b32_e32 v51, v0
	v_mov_b32_e32 v56, v0
	v_mov_b32_e32 v57, v0
	v_mov_b32_e32 v58, v0
	v_mov_b32_e32 v59, v0
	v_mov_b32_e32 v60, v0
	v_mov_b32_e32 v61, v0
	v_mov_b32_e32 v62, v0
	v_mov_b32_e32 v63, v0
	v_mov_b32_e32 v64, v0
	v_mov_b32_e32 v65, v0
	v_mov_b32_e32 v66, v0
	v_mov_b32_e32 v67, v0
	v_mov_b32_e32 v68, v0
	v_mov_b32_e32 v69, v0
	v_mov_b32_e32 v70, v0
	v_mov_b32_e32 v71, v0
	v_mov_b32_e32 v76, v0
	v_mov_b32_e32 v77, v0
	v_mov_b32_e32 v78, v0
	v_mov_b32_e32 v79, v0
	v_mov_b32_e32 v84, v0
	v_mov_b32_e32 v85, v0
	v_mov_b32_e32 v86, v0
	v_mov_b32_e32 v87, v0
	v_mov_b32_e32 v92, v0
	v_mov_b32_e32 v93, v0
	v_mov_b32_e32 v94, v0
	v_mov_b32_e32 v95, v0
	v_mov_b32_e32 v100, v0
	v_mov_b32_e32 v101, v0
	v_mov_b32_e32 v102, v0
	v_mov_b32_e32 v103, v0
	v_mov_b32_e32 v108, v0
	v_mov_b32_e32 v109, v0
	v_mov_b32_e32 v110, v0
	v_mov_b32_e32 v111, v0
	v_mov_b32_e32 v116, v0
	v_mov_b32_e32 v117, v0
	v_mov_b32_e32 v118, v0
	v_mov_b32_e32 v119, v0
	v_mov_b32_e32 v72, v0
	v_mov_b32_e32 v73, v0
	v_mov_b32_e32 v74, v0
	v_mov_b32_e32 v75, v0
	v_mov_b32_e32 v80, v0
	v_mov_b32_e32 v81, v0
	v_mov_b32_e32 v82, v0
	v_mov_b32_e32 v83, v0
	v_mov_b32_e32 v88, v0
	v_mov_b32_e32 v89, v0
	v_mov_b32_e32 v90, v0
	v_mov_b32_e32 v91, v0
	v_mov_b32_e32 v96, v0
	v_mov_b32_e32 v97, v0
	v_mov_b32_e32 v98, v0
	v_mov_b32_e32 v99, v0
	v_mov_b32_e32 v104, v0
	v_mov_b32_e32 v105, v0
	v_mov_b32_e32 v106, v0
	v_mov_b32_e32 v107, v0
	v_mov_b32_e32 v112, v0
	v_mov_b32_e32 v113, v0
	v_mov_b32_e32 v114, v0
	v_mov_b32_e32 v115, v0
	v_mov_b32_e32 v120, v0
	v_mov_b32_e32 v121, v0
	v_mov_b32_e32 v122, v0
	v_mov_b32_e32 v123, v0
	v_mov_b32_e32 v124, v0
	v_mov_b32_e32 v125, v0
	v_mov_b32_e32 v126, v0
	v_mov_b32_e32 v127, v0
	v_readlane_b32 vcc_lo, v246, 6
	s_nop 1
	s_cmp_lt_u32 vcc_lo, 4
	s_cbranch_scc0 .Lprio_204
	s_setprio 1

; template <class Epi, class Sched, bool ALIGN_EPI = false, bool SP2 = false>
; __device__ __forceinline__ void gemm_phase(PG8_LAS unsigned char* lds, const Gemm g, const Sched& S, const Epi& E, const int wid  ) {
;     ...
;         const unsigned nA = has_next ? (unsigned)g.asel(nxt.pn) * (unsigned)g.a_stride + (unsigned)nxt.pm * tstep : cA, nB = has_next ? (unsigned)nxt.pn * tstep : cB;
;         for (int t = 0; t < nt; t += 2) {
;             const bool last = (t == nt - 2);
;             const unsigned a1 = cA + (unsigned)(t + 1) * kstep;
;             const unsigned a2 = last ? nA : cA + (unsigned)(t + 2) * kstep, b2 = last ? nB : cB + (unsigned)(t + 2) * kstep;
;             const unsigned a3 = a2 + kstep, b3 = b2 + kstep;
;     ...
; #pragma unroll
;         for (int a = 0; a < 2; ++a)
; #pragma unroll
;             for (int b = 0; b < 2; ++b)
; #pragma unroll
;                 for (int m = 0; m < 4; ++m)
; #pragma unroll
;                     for (int n = 0; n < 2; ++n) acc[a][b][m][n] = (f32x4){0.f, 0.f, 0.f, 0.f};
;         cur = nxt; cA = nA; cB = nB; ++ui;
.LBB0_563:
	s_lshl_b32 s50, s49, 20
	s_and_b64 s[0:1], s[4:5], exec
	s_cselect_b32 s0, s50, s54
	s_lshl_b32 s51, s48, 20
	s_and_b64 s[14:15], s[4:5], exec
	v_mov_b32_e32 v0, 0
	s_cselect_b32 s1, s51, s55
	s_add_i32 s54, s54, 0x80080
	s_addk_i32 s55, 0x100
	s_mov_b32 s58, -2
	s_waitcnt lgkmcnt(0)
	v_mov_b32_e32 v1, v0
	v_mov_b32_e32 v2, v0
	v_mov_b32_e32 v3, v0
	v_mov_b32_e32 v4, v0
	v_mov_b32_e32 v5, v0
	v_mov_b32_e32 v6, v0
	v_mov_b32_e32 v7, v0
	v_mov_b32_e32 v16, v0
	v_mov_b32_e32 v17, v0
	v_mov_b32_e32 v18, v0
	v_mov_b32_e32 v19, v0
	v_mov_b32_e32 v20, v0
	v_mov_b32_e32 v21, v0
	v_mov_b32_e32 v22, v0
	v_mov_b32_e32 v23, v0
	v_mov_b32_e32 v32, v0
	v_mov_b32_e32 v33, v0
	v_mov_b32_e32 v34, v0
	v_mov_b32_e32 v35, v0
	v_mov_b32_e32 v36, v0
	v_mov_b32_e32 v37, v0
	v_mov_b32_e32 v38, v0
	v_mov_b32_e32 v39, v0
	v_mov_b32_e32 v48, v0
	v_mov_b32_e32 v49, v0
	v_mov_b32_e32 v50, v0
	v_mov_b32_e32 v51, v0
	v_mov_b32_e32 v52, v0
	v_mov_b32_e32 v53, v0
	v_mov_b32_e32 v54, v0
	v_mov_b32_e32 v55, v0
	v_mov_b32_e32 v8, v0
	v_mov_b32_e32 v9, v0
	v_mov_b32_e32 v10, v0
	v_mov_b32_e32 v11, v0
	v_mov_b32_e32 v12, v0
	v_mov_b32_e32 v13, v0
	v_mov_b32_e32 v14, v0
	v_mov_b32_e32 v15, v0
	v_mov_b32_e32 v24, v0
	v_mov_b32_e32 v25, v0
	v_mov_b32_e32 v26, v0
	v_mov_b32_e32 v27, v0
	v_mov_b32_e32 v28, v0
	v_mov_b32_e32 v29, v0
	v_mov_b32_e32 v30, v0
	v_mov_b32_e32 v31, v0
	v_mov_b32_e32 v40, v0
	v_mov_b32_e32 v41, v0
	v_mov_b32_e32 v42, v0
	v_mov_b32_e32 v43, v0
	v_mov_b32_e32 v44, v0
	v_mov_b32_e32 v45, v0
	v_mov_b32_e32 v46, v0
	v_mov_b32_e32 v47, v0
	v_mov_b32_e32 v56, v0
	v_mov_b32_e32 v57, v0
	v_mov_b32_e32 v58, v0
	v_mov_b32_e32 v59, v0
	v_mov_b32_e32 v60, v0
	v_mov_b32_e32 v61, v0
	v_mov_b32_e32 v62, v0
	v_mov_b32_e32 v63, v0
	v_mov_b32_e32 v64, v0
	v_mov_b32_e32 v65, v0
	v_mov_b32_e32 v66, v0
	v_mov_b32_e32 v67, v0
	v_mov_b32_e32 v68, v0
	v_mov_b32_e32 v69, v0
	v_mov_b32_e32 v70, v0
	v_mov_b32_e32 v71, v0
	v_mov_b32_e32 v80, v0
	v_mov_b32_e32 v81, v0
	v_mov_b32_e32 v82, v0
	v_mov_b32_e32 v83, v0
	v_mov_b32_e32 v84, v0
	v_mov_b32_e32 v85, v0
	v_mov_b32_e32 v86, v0
	v_mov_b32_e32 v87, v0
	v_mov_b32_e32 v96, v0
	v_mov_b32_e32 v97, v0
	v_mov_b32_e32 v98, v0
	v_mov_b32_e32 v99, v0
	v_mov_b32_e32 v100, v0
	v_mov_b32_e32 v101, v0
	v_mov_b32_e32 v102, v0
	v_mov_b32_e32 v103, v0
	v_mov_b32_e32 v112, v0
	v_mov_b32_e32 v113, v0
	v_mov_b32_e32 v114, v0
	v_mov_b32_e32 v115, v0
	v_mov_b32_e32 v116, v0
	v_mov_b32_e32 v117, v0
	v_mov_b32_e32 v118, v0
	v_mov_b32_e32 v119, v0
	v_mov_b32_e32 v72, v0
	v_mov_b32_e32 v73, v0
	v_mov_b32_e32 v74, v0
	v_mov_b32_e32 v75, v0
	v_mov_b32_e32 v76, v0
	v_mov_b32_e32 v77, v0
	v_mov_b32_e32 v78, v0
	v_mov_b32_e32 v79, v0
	v_mov_b32_e32 v88, v0
	v_mov_b32_e32 v89, v0
	v_mov_b32_e32 v90, v0
	v_mov_b32_e32 v91, v0
	v_mov_b32_e32 v92, v0
	v_mov_b32_e32 v93, v0
	v_mov_b32_e32 v94, v0
	v_mov_b32_e32 v95, v0
	v_mov_b32_e32 v104, v0
	v_mov_b32_e32 v105, v0
	v_mov_b32_e32 v106, v0
	v_mov_b32_e32 v107, v0
	v_mov_b32_e32 v108, v0
	v_mov_b32_e32 v109, v0
	v_mov_b32_e32 v110, v0
	v_mov_b32_e32 v111, v0
	v_mov_b32_e32 v120, v0
	v_mov_b32_e32 v121, v0
	v_mov_b32_e32 v122, v0
	v_mov_b32_e32 v123, v0
	v_mov_b32_e32 v124, v0
	v_mov_b32_e32 v125, v0
	v_mov_b32_e32 v126, v0
	v_mov_b32_e32 v127, v0
	v_readlane_b32 vcc_lo, v246, 6
	s_nop 1
	s_cmp_lt_u32 vcc_lo, 4
	s_cbranch_scc0 .Lprio_564
	s_setprio 1

; template <class Epi, class Sched, bool ALIGN_EPI = false, bool SP2 = false>
; __device__ __forceinline__ void gemm_phase(PG8_LAS unsigned char* lds, const Gemm g, const Sched& S, const Epi& E, const int wid  ) {
;     ...
;         const unsigned nA = has_next ? (unsigned)g.asel(nxt.pn) * (unsigned)g.a_stride + (unsigned)nxt.pm * tstep : cA, nB = has_next ? (unsigned)nxt.pn * tstep : cB;
;         for (int t = 0; t < nt; t += 2) {
;             const bool last = (t == nt - 2);
;             const unsigned a1 = cA + (unsigned)(t + 1) * kstep;
;             const unsigned a2 = last ? nA : cA + (unsigned)(t + 2) * kstep, b2 = last ? nB : cB + (unsigned)(t + 2) * kstep;
;             const unsigned a3 = a2 + kstep, b3 = b2 + kstep;
;     ...
; #pragma unroll
;         for (int a = 0; a < 2; ++a)
; #pragma unroll
;             for (int b = 0; b < 2; ++b)
; #pragma unroll
;                 for (int m = 0; m < 4; ++m)
; #pragma unroll
;                     for (int n = 0; n < 2; ++n) acc[a][b][m][n] = (f32x4){0.f, 0.f, 0.f, 0.f};
;         cur = nxt; cA = nA; cB = nB; ++ui;
.LBB0_657:
	s_lshl_b32 s91, s90, 20
	s_and_b64 s[6:7], s[4:5], exec
	s_cselect_b32 s6, s91, s8
	s_lshl_b32 s92, s89, 20
	s_and_b64 s[18:19], s[4:5], exec
	v_mov_b32_e32 v56, 0
	s_cselect_b32 s7, s92, s9
	s_add_i32 s8, s8, 0x80080
	s_addk_i32 s9, 0x100
	s_mov_b32 s46, -2
	v_mov_b32_e32 v57, v56
	v_mov_b32_e32 v58, v56
	v_mov_b32_e32 v59, v56
	v_mov_b32_e32 v60, v56
	v_mov_b32_e32 v61, v56
	v_mov_b32_e32 v62, v56
	v_mov_b32_e32 v63, v56
	v_mov_b32_e32 v64, v56
	v_mov_b32_e32 v65, v56
	v_mov_b32_e32 v66, v56
	v_mov_b32_e32 v67, v56
	v_mov_b32_e32 v68, v56
	v_mov_b32_e32 v69, v56
	v_mov_b32_e32 v70, v56
	v_mov_b32_e32 v71, v56
	v_mov_b32_e32 v72, v56
	v_mov_b32_e32 v73, v56
	v_mov_b32_e32 v74, v56
	v_mov_b32_e32 v75, v56
	v_mov_b32_e32 v80, v56
	v_mov_b32_e32 v81, v56
	v_mov_b32_e32 v82, v56
	v_mov_b32_e32 v83, v56
	v_mov_b32_e32 v0, v56
	v_mov_b32_e32 v1, v56
	s_waitcnt lgkmcnt(7)
	v_mov_b32_e32 v2, v56
	v_mov_b32_e32 v3, v56
	s_waitcnt lgkmcnt(6)
	v_mov_b32_e32 v4, v56
	v_mov_b32_e32 v5, v56
	s_waitcnt lgkmcnt(5)
	v_mov_b32_e32 v6, v56
	v_mov_b32_e32 v7, v56
	v_mov_b32_e32 v48, v56
	v_mov_b32_e32 v49, v56
	v_mov_b32_e32 v50, v56
	v_mov_b32_e32 v51, v56
	v_mov_b32_e32 v92, v56
	v_mov_b32_e32 v93, v56
	v_mov_b32_e32 v94, v56
	v_mov_b32_e32 v95, v56
	v_mov_b32_e32 v76, v56
	v_mov_b32_e32 v77, v56
	v_mov_b32_e32 v78, v56
	v_mov_b32_e32 v79, v56
	v_mov_b32_e32 v84, v56
	v_mov_b32_e32 v85, v56
	v_mov_b32_e32 v86, v56
	v_mov_b32_e32 v87, v56
	v_mov_b32_e32 v88, v56
	v_mov_b32_e32 v89, v56
	v_mov_b32_e32 v90, v56
	v_mov_b32_e32 v91, v56
	v_mov_b32_e32 v96, v56
	v_mov_b32_e32 v97, v56
	v_mov_b32_e32 v98, v56
	v_mov_b32_e32 v99, v56
	v_mov_b32_e32 v100, v56
	v_mov_b32_e32 v101, v56
	v_mov_b32_e32 v102, v56
	v_mov_b32_e32 v103, v56
	v_mov_b32_e32 v104, v56
	v_mov_b32_e32 v105, v56
	v_mov_b32_e32 v106, v56
	v_mov_b32_e32 v107, v56
	v_mov_b32_e32 v108, v56
	v_mov_b32_e32 v109, v56
	v_mov_b32_e32 v110, v56
	v_mov_b32_e32 v111, v56
	v_mov_b32_e32 v112, v56
	v_mov_b32_e32 v113, v56
	v_mov_b32_e32 v114, v56
	v_mov_b32_e32 v115, v56
	v_mov_b32_e32 v116, v56
	v_mov_b32_e32 v117, v56
	v_mov_b32_e32 v118, v56
	v_mov_b32_e32 v119, v56
	v_mov_b32_e32 v124, v56
	v_mov_b32_e32 v125, v56
	v_mov_b32_e32 v126, v56
	v_mov_b32_e32 v127, v56
	v_mov_b32_e32 v128, v56
	v_mov_b32_e32 v129, v56
	v_mov_b32_e32 v130, v56
	v_mov_b32_e32 v131, v56
	v_mov_b32_e32 v136, v56
	v_mov_b32_e32 v137, v56
	v_mov_b32_e32 v138, v56
	v_mov_b32_e32 v139, v56
	s_waitcnt lgkmcnt(4)
	v_mov_b32_e32 v8, v56
	v_mov_b32_e32 v9, v56
	s_waitcnt lgkmcnt(3)
	v_mov_b32_e32 v10, v56
	v_mov_b32_e32 v11, v56
	s_waitcnt lgkmcnt(2)
	v_mov_b32_e32 v12, v56
	v_mov_b32_e32 v13, v56
	s_waitcnt lgkmcnt(1)
	v_mov_b32_e32 v14, v56
	v_mov_b32_e32 v15, v56
	v_mov_b32_e32 v120, v56
	v_mov_b32_e32 v121, v56
	v_mov_b32_e32 v122, v56
	v_mov_b32_e32 v123, v56
	v_mov_b32_e32 v156, v56
	v_mov_b32_e32 v157, v56
	v_mov_b32_e32 v158, v56
	v_mov_b32_e32 v159, v56
	v_mov_b32_e32 v132, v56
	v_mov_b32_e32 v133, v56
	v_mov_b32_e32 v134, v56
	v_mov_b32_e32 v135, v56
	v_mov_b32_e32 v140, v56
	v_mov_b32_e32 v141, v56
	v_mov_b32_e32 v142, v56
	v_mov_b32_e32 v143, v56
	v_mov_b32_e32 v144, v56
	v_mov_b32_e32 v145, v56
	v_mov_b32_e32 v146, v56
	v_mov_b32_e32 v147, v56
	v_mov_b32_e32 v148, v56
	v_mov_b32_e32 v149, v56
	v_mov_b32_e32 v150, v56
	v_mov_b32_e32 v151, v56
	v_mov_b32_e32 v52, v56
	v_mov_b32_e32 v53, v56
	v_mov_b32_e32 v54, v56
	v_mov_b32_e32 v55, v56
	v_mov_b32_e32 v152, v56
	v_mov_b32_e32 v153, v56
	v_mov_b32_e32 v154, v56
	v_mov_b32_e32 v155, v56
	v_readlane_b32 vcc_lo, v246, 6
	s_nop 1
	s_cmp_lt_u32 vcc_lo, 4
	s_cbranch_scc0 .Lprio_658
	s_setprio 1

; template <class Epi, class Sched, bool ALIGN_EPI = false, bool SP2 = false>
; __device__ __forceinline__ void gemm_phase(PG8_LAS unsigned char* lds, const Gemm g, const Sched& S, const Epi& E, const int wid  ) {
;     ...
;         const unsigned nA = has_next ? (unsigned)g.asel(nxt.pn) * (unsigned)g.a_stride + (unsigned)nxt.pm * tstep : cA, nB = has_next ? (unsigned)nxt.pn * tstep : cB;
;         for (int t = 0; t < nt; t += 2) {
;             const bool last = (t == nt - 2);
;             const unsigned a1 = cA + (unsigned)(t + 1) * kstep;
;             const unsigned a2 = last ? nA : cA + (unsigned)(t + 2) * kstep, b2 = last ? nB : cB + (unsigned)(t + 2) * kstep;
;             const unsigned a3 = a2 + kstep, b3 = b2 + kstep;
;     ...
; #pragma unroll
;         for (int a = 0; a < 2; ++a)
; #pragma unroll
;             for (int b = 0; b < 2; ++b)
; #pragma unroll
;                 for (int m = 0; m < 4; ++m)
; #pragma unroll
;                     for (int n = 0; n < 2; ++n) acc[a][b][m][n] = (f32x4){0.f, 0.f, 0.f, 0.f};
;         cur = nxt; cA = nA; cB = nB; ++ui;
.LBB0_803:
	s_mul_i32 s50, s49, 0x2c0000
	s_and_b64 s[0:1], s[4:5], exec
	s_mul_i32 s51, s48, 0x2c0000
	v_mov_b32_e32 v0, 0
	s_cselect_b32 s0, s50, s54
	s_cselect_b32 s1, s51, s55
	s_add_i32 s54, s54, 0x160080
	s_addk_i32 s55, 0x100
	s_mov_b32 s58, -2
	s_waitcnt lgkmcnt(0)
	v_mov_b32_e32 v1, v0
	v_mov_b32_e32 v2, v0
	v_mov_b32_e32 v3, v0
	v_mov_b32_e32 v4, v0
	v_mov_b32_e32 v5, v0
	v_mov_b32_e32 v6, v0
	v_mov_b32_e32 v7, v0
	v_mov_b32_e32 v16, v0
	v_mov_b32_e32 v17, v0
	v_mov_b32_e32 v18, v0
	v_mov_b32_e32 v19, v0
	v_mov_b32_e32 v20, v0
	v_mov_b32_e32 v21, v0
	v_mov_b32_e32 v22, v0
	v_mov_b32_e32 v23, v0
	v_mov_b32_e32 v32, v0
	v_mov_b32_e32 v33, v0
	v_mov_b32_e32 v34, v0
	v_mov_b32_e32 v35, v0
	v_mov_b32_e32 v36, v0
	v_mov_b32_e32 v37, v0
	v_mov_b32_e32 v38, v0
	v_mov_b32_e32 v39, v0
	v_mov_b32_e32 v48, v0
	v_mov_b32_e32 v49, v0
	v_mov_b32_e32 v50, v0
	v_mov_b32_e32 v51, v0
	v_mov_b32_e32 v52, v0
	v_mov_b32_e32 v53, v0
	v_mov_b32_e32 v54, v0
	v_mov_b32_e32 v55, v0
	v_mov_b32_e32 v8, v0
	v_mov_b32_e32 v9, v0
	v_mov_b32_e32 v10, v0
	v_mov_b32_e32 v11, v0
	v_mov_b32_e32 v12, v0
	v_mov_b32_e32 v13, v0
	v_mov_b32_e32 v14, v0
	v_mov_b32_e32 v15, v0
	v_mov_b32_e32 v24, v0
	v_mov_b32_e32 v25, v0
	v_mov_b32_e32 v26, v0
	v_mov_b32_e32 v27, v0
	v_mov_b32_e32 v28, v0
	v_mov_b32_e32 v29, v0
	v_mov_b32_e32 v30, v0
	v_mov_b32_e32 v31, v0
	v_mov_b32_e32 v40, v0
	v_mov_b32_e32 v41, v0
	v_mov_b32_e32 v42, v0
	v_mov_b32_e32 v43, v0
	v_mov_b32_e32 v44, v0
	v_mov_b32_e32 v45, v0
	v_mov_b32_e32 v46, v0
	v_mov_b32_e32 v47, v0
	v_mov_b32_e32 v56, v0
	v_mov_b32_e32 v57, v0
	v_mov_b32_e32 v58, v0
	v_mov_b32_e32 v59, v0
	v_mov_b32_e32 v60, v0
	v_mov_b32_e32 v61, v0
	v_mov_b32_e32 v62, v0
	v_mov_b32_e32 v63, v0
	v_mov_b32_e32 v64, v0
	v_mov_b32_e32 v65, v0
	v_mov_b32_e32 v66, v0
	v_mov_b32_e32 v67, v0
	v_mov_b32_e32 v68, v0
	v_mov_b32_e32 v69, v0
	v_mov_b32_e32 v70, v0
	v_mov_b32_e32 v71, v0
	v_mov_b32_e32 v80, v0
	v_mov_b32_e32 v81, v0
	v_mov_b32_e32 v82, v0
	v_mov_b32_e32 v83, v0
	v_mov_b32_e32 v84, v0
	v_mov_b32_e32 v85, v0
	v_mov_b32_e32 v86, v0
	v_mov_b32_e32 v87, v0
	v_mov_b32_e32 v96, v0
	v_mov_b32_e32 v97, v0
	v_mov_b32_e32 v98, v0
	v_mov_b32_e32 v99, v0
	v_mov_b32_e32 v100, v0
	v_mov_b32_e32 v101, v0
	v_mov_b32_e32 v102, v0
	v_mov_b32_e32 v103, v0
	v_mov_b32_e32 v112, v0
	v_mov_b32_e32 v113, v0
	v_mov_b32_e32 v114, v0
	v_mov_b32_e32 v115, v0
	v_mov_b32_e32 v116, v0
	v_mov_b32_e32 v117, v0
	v_mov_b32_e32 v118, v0
	v_mov_b32_e32 v119, v0
	v_mov_b32_e32 v72, v0
	v_mov_b32_e32 v73, v0
	v_mov_b32_e32 v74, v0
	v_mov_b32_e32 v75, v0
	v_mov_b32_e32 v76, v0
	v_mov_b32_e32 v77, v0
	v_mov_b32_e32 v78, v0
	v_mov_b32_e32 v79, v0
	v_mov_b32_e32 v88, v0
	v_mov_b32_e32 v89, v0
	v_mov_b32_e32 v90, v0
	v_mov_b32_e32 v91, v0
	v_mov_b32_e32 v92, v0
	v_mov_b32_e32 v93, v0
	v_mov_b32_e32 v94, v0
	v_mov_b32_e32 v95, v0
	v_mov_b32_e32 v104, v0
	v_mov_b32_e32 v105, v0
	v_mov_b32_e32 v106, v0
	v_mov_b32_e32 v107, v0
	v_mov_b32_e32 v108, v0
	v_mov_b32_e32 v109, v0
	v_mov_b32_e32 v110, v0
	v_mov_b32_e32 v111, v0
	v_mov_b32_e32 v120, v0
	v_mov_b32_e32 v121, v0
	v_mov_b32_e32 v122, v0
	v_mov_b32_e32 v123, v0
	v_mov_b32_e32 v124, v0
	v_mov_b32_e32 v125, v0
	v_mov_b32_e32 v126, v0
	v_mov_b32_e32 v127, v0
	v_readlane_b32 vcc_lo, v246, 6
	s_nop 1
	s_cmp_lt_u32 vcc_lo, 4
	s_cbranch_scc0 .Lprio_804
	s_setprio 1

; template <class Epi, class Sched, bool ALIGN_EPI = false, bool SP2 = false>
; __device__ __forceinline__ void gemm_phase(PG8_LAS unsigned char* lds, const Gemm g, const Sched& S, const Epi& E, const int wid  ) {
;     ...
;         const unsigned nA = has_next ? (unsigned)g.asel(nxt.pn) * (unsigned)g.a_stride + (unsigned)nxt.pm * tstep : cA, nB = has_next ? (unsigned)nxt.pn * tstep : cB;
;         for (int t = 0; t < nt; t += 2) {
;             const bool last = (t == nt - 2);
;             const unsigned a1 = cA + (unsigned)(t + 1) * kstep;
;             const unsigned a2 = last ? nA : cA + (unsigned)(t + 2) * kstep, b2 = last ? nB : cB + (unsigned)(t + 2) * kstep;
;             const unsigned a3 = a2 + kstep, b3 = b2 + kstep;
;     ...
; #pragma unroll
;         for (int a = 0; a < 2; ++a)
; #pragma unroll
;             for (int b = 0; b < 2; ++b)
; #pragma unroll
;                 for (int m = 0; m < 4; ++m)
; #pragma unroll
;                     for (int n = 0; n < 2; ++n) acc[a][b][m][n] = (f32x4){0.f, 0.f, 0.f, 0.f};
;         cur = nxt; cA = nA; cB = nB; ++ui;
.LBB0_902:
	s_lshl_b32 s70, s69, 20
	s_and_b64 s[14:15], s[4:5], exec
	s_cselect_b32 s33, s70, s41
	s_lshl_b32 s71, s68, 20
	s_and_b64 s[14:15], s[4:5], exec
	v_mov_b32_e32 v0, 0
	s_cselect_b32 s40, s71, s74
	s_add_i32 s41, s41, 0x80080
	s_addk_i32 s74, 0x100
	s_mov_b32 s75, -2
	s_waitcnt lgkmcnt(0)
	v_mov_b32_e32 v1, v0
	v_mov_b32_e32 v2, v0
	v_mov_b32_e32 v3, v0
	v_mov_b32_e32 v4, v0
	v_mov_b32_e32 v5, v0
	s_waitcnt lgkmcnt(6)
	v_mov_b32_e32 v6, v0
	v_mov_b32_e32 v7, v0
	s_waitcnt lgkmcnt(1)
	v_mov_b32_e32 v16, v0
	v_mov_b32_e32 v17, v0
	s_waitcnt lgkmcnt(0)
	v_mov_b32_e32 v18, v0
	v_mov_b32_e32 v19, v0
	v_mov_b32_e32 v20, v0
	v_mov_b32_e32 v21, v0
	v_mov_b32_e32 v22, v0
	v_mov_b32_e32 v23, v0
	v_mov_b32_e32 v32, v0
	v_mov_b32_e32 v33, v0
	v_mov_b32_e32 v34, v0
	v_mov_b32_e32 v35, v0
	v_mov_b32_e32 v36, v0
	v_mov_b32_e32 v37, v0
	v_mov_b32_e32 v38, v0
	v_mov_b32_e32 v39, v0
	v_mov_b32_e32 v48, v0
	v_mov_b32_e32 v49, v0
	v_mov_b32_e32 v50, v0
	v_mov_b32_e32 v51, v0
	v_mov_b32_e32 v52, v0
	v_mov_b32_e32 v53, v0
	v_mov_b32_e32 v54, v0
	v_mov_b32_e32 v55, v0
	v_mov_b32_e32 v8, v0
	v_mov_b32_e32 v9, v0
	v_mov_b32_e32 v10, v0
	v_mov_b32_e32 v11, v0
	v_mov_b32_e32 v12, v0
	v_mov_b32_e32 v13, v0
	v_mov_b32_e32 v14, v0
	v_mov_b32_e32 v15, v0
	v_mov_b32_e32 v24, v0
	v_mov_b32_e32 v25, v0
	v_mov_b32_e32 v26, v0
	v_mov_b32_e32 v27, v0
	v_mov_b32_e32 v28, v0
	v_mov_b32_e32 v29, v0
	v_mov_b32_e32 v30, v0
	v_mov_b32_e32 v31, v0
	v_mov_b32_e32 v40, v0
	v_mov_b32_e32 v41, v0
	v_mov_b32_e32 v42, v0
	v_mov_b32_e32 v43, v0
	v_mov_b32_e32 v44, v0
	v_mov_b32_e32 v45, v0
	v_mov_b32_e32 v46, v0
	v_mov_b32_e32 v47, v0
	v_mov_b32_e32 v56, v0
	v_mov_b32_e32 v57, v0
	v_mov_b32_e32 v58, v0
	v_mov_b32_e32 v59, v0
	v_mov_b32_e32 v60, v0
	v_mov_b32_e32 v61, v0
	v_mov_b32_e32 v62, v0
	v_mov_b32_e32 v63, v0
	v_mov_b32_e32 v64, v0
	v_mov_b32_e32 v65, v0
	v_mov_b32_e32 v66, v0
	v_mov_b32_e32 v67, v0
	v_mov_b32_e32 v68, v0
	v_mov_b32_e32 v69, v0
	v_mov_b32_e32 v70, v0
	v_mov_b32_e32 v71, v0
	v_mov_b32_e32 v80, v0
	v_mov_b32_e32 v81, v0
	v_mov_b32_e32 v82, v0
	v_mov_b32_e32 v83, v0
	v_mov_b32_e32 v84, v0
	v_mov_b32_e32 v85, v0
	v_mov_b32_e32 v86, v0
	v_mov_b32_e32 v87, v0
	v_mov_b32_e32 v96, v0
	v_mov_b32_e32 v97, v0
	v_mov_b32_e32 v98, v0
	v_mov_b32_e32 v99, v0
	v_mov_b32_e32 v100, v0
	v_mov_b32_e32 v101, v0
	v_mov_b32_e32 v102, v0
	v_mov_b32_e32 v103, v0
	v_mov_b32_e32 v112, v0
	v_mov_b32_e32 v113, v0
	v_mov_b32_e32 v114, v0
	v_mov_b32_e32 v115, v0
	v_mov_b32_e32 v116, v0
	v_mov_b32_e32 v117, v0
	v_mov_b32_e32 v118, v0
	v_mov_b32_e32 v119, v0
	v_mov_b32_e32 v72, v0
	v_mov_b32_e32 v73, v0
	v_mov_b32_e32 v74, v0
	v_mov_b32_e32 v75, v0
	v_mov_b32_e32 v76, v0
	v_mov_b32_e32 v77, v0
	v_mov_b32_e32 v78, v0
	v_mov_b32_e32 v79, v0
	v_mov_b32_e32 v88, v0
	v_mov_b32_e32 v89, v0
	v_mov_b32_e32 v90, v0
	v_mov_b32_e32 v91, v0
	v_mov_b32_e32 v92, v0
	v_mov_b32_e32 v93, v0
	v_mov_b32_e32 v94, v0
	v_mov_b32_e32 v95, v0
	v_mov_b32_e32 v104, v0
	v_mov_b32_e32 v105, v0
	v_mov_b32_e32 v106, v0
	v_mov_b32_e32 v107, v0
	v_mov_b32_e32 v108, v0
	v_mov_b32_e32 v109, v0
	v_mov_b32_e32 v110, v0
	v_mov_b32_e32 v111, v0
	v_mov_b32_e32 v120, v0
	v_mov_b32_e32 v121, v0
	v_mov_b32_e32 v122, v0
	v_mov_b32_e32 v123, v0
	v_mov_b32_e32 v124, v0
	v_mov_b32_e32 v125, v0
	v_mov_b32_e32 v126, v0
	v_mov_b32_e32 v127, v0
	v_readlane_b32 vcc_lo, v246, 6
	s_nop 1
	s_cmp_lt_u32 vcc_lo, 4
	s_cbranch_scc0 .Lprio_903
	s_setprio 1

; template <class Epi, class Sched, bool ALIGN_EPI = false, bool SP2 = false>
; __device__ __forceinline__ void gemm_phase(PG8_LAS unsigned char* lds, const Gemm g, const Sched& S, const Epi& E, const int wid  ) {
;     ...
;         const unsigned nA = has_next ? (unsigned)g.asel(nxt.pn) * (unsigned)g.a_stride + (unsigned)nxt.pm * tstep : cA, nB = has_next ? (unsigned)nxt.pn * tstep : cB;
;         for (int t = 0; t < nt; t += 2) {
;             const bool last = (t == nt - 2);
;             const unsigned a1 = cA + (unsigned)(t + 1) * kstep;
;             const unsigned a2 = last ? nA : cA + (unsigned)(t + 2) * kstep, b2 = last ? nB : cB + (unsigned)(t + 2) * kstep;
;             const unsigned a3 = a2 + kstep, b3 = b2 + kstep;
;     ...
; #pragma unroll
;         for (int a = 0; a < 2; ++a)
; #pragma unroll
;             for (int b = 0; b < 2; ++b)
; #pragma unroll
;                 for (int m = 0; m < 4; ++m)
; #pragma unroll
;                     for (int n = 0; n < 2; ++n) acc[a][b][m][n] = (f32x4){0.f, 0.f, 0.f, 0.f};
;         cur = nxt; cA = nA; cB = nB; ++ui;
.LBB0_1075:
	s_lshl_b32 s58, s51, 20
	s_and_b64 s[0:1], s[0:1], exec
	v_mov_b32_e32 v0, 0
	s_cselect_b32 s0, s58, s16
	s_add_i32 s1, s20, 0x80080
	s_addk_i32 s16, 0x100
	s_mov_b32 s20, -2
	v_mov_b32_e32 v1, v0
	v_mov_b32_e32 v2, v0
	v_mov_b32_e32 v3, v0
	v_mov_b32_e32 v4, v0
	v_mov_b32_e32 v5, v0
	v_mov_b32_e32 v6, v0
	v_mov_b32_e32 v7, v0
	v_mov_b32_e32 v16, v0
	v_mov_b32_e32 v17, v0
	v_mov_b32_e32 v18, v0
	v_mov_b32_e32 v19, v0
	v_mov_b32_e32 v20, v0
	v_mov_b32_e32 v21, v0
	v_mov_b32_e32 v22, v0
	v_mov_b32_e32 v23, v0
	v_mov_b32_e32 v32, v0
	v_mov_b32_e32 v33, v0
	v_mov_b32_e32 v34, v0
	v_mov_b32_e32 v35, v0
	v_mov_b32_e32 v36, v0
	v_mov_b32_e32 v37, v0
	v_mov_b32_e32 v38, v0
	v_mov_b32_e32 v39, v0
	v_mov_b32_e32 v48, v0
	v_mov_b32_e32 v49, v0
	v_mov_b32_e32 v50, v0
	v_mov_b32_e32 v51, v0
	v_mov_b32_e32 v52, v0
	v_mov_b32_e32 v53, v0
	v_mov_b32_e32 v54, v0
	v_mov_b32_e32 v55, v0
	v_mov_b32_e32 v8, v0
	v_mov_b32_e32 v9, v0
	v_mov_b32_e32 v10, v0
	v_mov_b32_e32 v11, v0
	v_mov_b32_e32 v12, v0
	v_mov_b32_e32 v13, v0
	v_mov_b32_e32 v14, v0
	v_mov_b32_e32 v15, v0
	v_mov_b32_e32 v24, v0
	v_mov_b32_e32 v25, v0
	v_mov_b32_e32 v26, v0
	v_mov_b32_e32 v27, v0
	v_mov_b32_e32 v28, v0
	v_mov_b32_e32 v29, v0
	v_mov_b32_e32 v30, v0
	v_mov_b32_e32 v31, v0
	v_mov_b32_e32 v40, v0
	v_mov_b32_e32 v41, v0
	v_mov_b32_e32 v42, v0
	v_mov_b32_e32 v43, v0
	v_mov_b32_e32 v44, v0
	v_mov_b32_e32 v45, v0
	v_mov_b32_e32 v46, v0
	v_mov_b32_e32 v47, v0
	v_mov_b32_e32 v56, v0
	v_mov_b32_e32 v57, v0
	v_mov_b32_e32 v58, v0
	v_mov_b32_e32 v59, v0
	v_mov_b32_e32 v60, v0
	v_mov_b32_e32 v61, v0
	v_mov_b32_e32 v62, v0
	v_mov_b32_e32 v63, v0
	v_mov_b32_e32 v64, v0
	v_mov_b32_e32 v65, v0
	v_mov_b32_e32 v66, v0
	v_mov_b32_e32 v67, v0
	v_mov_b32_e32 v68, v0
	v_mov_b32_e32 v69, v0
	v_mov_b32_e32 v70, v0
	v_mov_b32_e32 v71, v0
	v_mov_b32_e32 v80, v0
	v_mov_b32_e32 v81, v0
	v_mov_b32_e32 v82, v0
	v_mov_b32_e32 v83, v0
	v_mov_b32_e32 v84, v0
	v_mov_b32_e32 v85, v0
	v_mov_b32_e32 v86, v0
	v_mov_b32_e32 v87, v0
	v_mov_b32_e32 v96, v0
	v_mov_b32_e32 v97, v0
	v_mov_b32_e32 v98, v0
	v_mov_b32_e32 v99, v0
	v_mov_b32_e32 v100, v0
	v_mov_b32_e32 v101, v0
	v_mov_b32_e32 v102, v0
	v_mov_b32_e32 v103, v0
	v_mov_b32_e32 v112, v0
	v_mov_b32_e32 v113, v0
	v_mov_b32_e32 v114, v0
	v_mov_b32_e32 v115, v0
	v_mov_b32_e32 v116, v0
	v_mov_b32_e32 v117, v0
	v_mov_b32_e32 v118, v0
	v_mov_b32_e32 v119, v0
	v_mov_b32_e32 v72, v0
	v_mov_b32_e32 v73, v0
	v_mov_b32_e32 v74, v0
	v_mov_b32_e32 v75, v0
	v_mov_b32_e32 v76, v0
	v_mov_b32_e32 v77, v0
	v_mov_b32_e32 v78, v0
	v_mov_b32_e32 v79, v0
	v_mov_b32_e32 v88, v0
	v_mov_b32_e32 v89, v0
	v_mov_b32_e32 v90, v0
	v_mov_b32_e32 v91, v0
	v_mov_b32_e32 v92, v0
	v_mov_b32_e32 v93, v0
	v_mov_b32_e32 v94, v0
	v_mov_b32_e32 v95, v0
	v_mov_b32_e32 v104, v0
	v_mov_b32_e32 v105, v0
	v_mov_b32_e32 v106, v0
	v_mov_b32_e32 v107, v0
	v_mov_b32_e32 v108, v0
	v_mov_b32_e32 v109, v0
	v_mov_b32_e32 v110, v0
	v_mov_b32_e32 v111, v0
	v_mov_b32_e32 v120, v0
	v_mov_b32_e32 v121, v0
	v_mov_b32_e32 v122, v0
	v_mov_b32_e32 v123, v0
	v_mov_b32_e32 v124, v0
	v_mov_b32_e32 v125, v0
	v_mov_b32_e32 v126, v0
	v_mov_b32_e32 v127, v0
	v_readlane_b32 vcc_lo, v246, 6
	s_nop 1
	s_cmp_lt_u32 vcc_lo, 4
	s_cbranch_scc0 .Lprio_1076
	s_setprio 1

; template <class Epi, class Sched, bool ALIGN_EPI = false, bool SP2 = false>
; __device__ __forceinline__ void gemm_phase(PG8_LAS unsigned char* lds, const Gemm g, const Sched& S, const Epi& E, const int wid  ) {
;     ...
;         const unsigned nA = has_next ? (unsigned)g.asel(nxt.pn) * (unsigned)g.a_stride + (unsigned)nxt.pm * tstep : cA, nB = has_next ? (unsigned)nxt.pn * tstep : cB;
;         for (int t = 0; t < nt; t += 2) {
;             const bool last = (t == nt - 2);
;             const unsigned a1 = cA + (unsigned)(t + 1) * kstep;
;             const unsigned a2 = last ? nA : cA + (unsigned)(t + 2) * kstep, b2 = last ? nB : cB + (unsigned)(t + 2) * kstep;
;             const unsigned a3 = a2 + kstep, b3 = b2 + kstep;
;     ...
; #pragma unroll
;         for (int a = 0; a < 2; ++a)
; #pragma unroll
;             for (int b = 0; b < 2; ++b)
; #pragma unroll
;                 for (int m = 0; m < 4; ++m)
; #pragma unroll
;                     for (int n = 0; n < 2; ++n) acc[a][b][m][n] = (f32x4){0.f, 0.f, 0.f, 0.f};
;         cur = nxt; cA = nA; cB = nB; ++ui;
.LBB0_1942:
	s_lshl_b32 s50, s49, 20
	s_and_b64 s[0:1], s[4:5], exec
	s_cselect_b32 s0, s50, s54
	s_lshl_b32 s51, s48, 20
	s_and_b64 s[14:15], s[4:5], exec
	v_mov_b32_e32 v0, 0
	s_cselect_b32 s1, s51, s55
	s_add_i32 s54, s54, 0x80080
	s_addk_i32 s55, 0x100
	s_mov_b32 s58, -2
	s_waitcnt lgkmcnt(0)
	v_mov_b32_e32 v1, v0
	v_mov_b32_e32 v2, v0
	v_mov_b32_e32 v3, v0
	v_mov_b32_e32 v4, v0
	v_mov_b32_e32 v5, v0
	v_mov_b32_e32 v6, v0
	v_mov_b32_e32 v7, v0
	v_mov_b32_e32 v16, v0
	v_mov_b32_e32 v17, v0
	v_mov_b32_e32 v18, v0
	v_mov_b32_e32 v19, v0
	s_waitcnt vmcnt(21)
	v_mov_b32_e32 v20, v0
	v_mov_b32_e32 v21, v0
	v_mov_b32_e32 v22, v0
	v_mov_b32_e32 v23, v0
	v_mov_b32_e32 v32, v0
	v_mov_b32_e32 v33, v0
	v_mov_b32_e32 v34, v0
	v_mov_b32_e32 v35, v0
	v_mov_b32_e32 v36, v0
	v_mov_b32_e32 v37, v0
	v_mov_b32_e32 v38, v0
	v_mov_b32_e32 v39, v0
	v_mov_b32_e32 v48, v0
	v_mov_b32_e32 v49, v0
	s_waitcnt vmcnt(16)
	v_mov_b32_e32 v50, v0
	v_mov_b32_e32 v51, v0
	v_mov_b32_e32 v52, v0
	v_mov_b32_e32 v53, v0
	v_mov_b32_e32 v54, v0
	v_mov_b32_e32 v55, v0
	v_mov_b32_e32 v8, v0
	v_mov_b32_e32 v9, v0
	v_mov_b32_e32 v10, v0
	v_mov_b32_e32 v11, v0
	v_mov_b32_e32 v12, v0
	v_mov_b32_e32 v13, v0
	v_mov_b32_e32 v14, v0
	v_mov_b32_e32 v15, v0
	v_mov_b32_e32 v24, v0
	v_mov_b32_e32 v25, v0
	v_mov_b32_e32 v26, v0
	v_mov_b32_e32 v27, v0
	v_mov_b32_e32 v28, v0
	v_mov_b32_e32 v29, v0
	v_mov_b32_e32 v30, v0
	v_mov_b32_e32 v31, v0
	v_mov_b32_e32 v40, v0
	v_mov_b32_e32 v41, v0
	v_mov_b32_e32 v42, v0
	v_mov_b32_e32 v43, v0
	v_mov_b32_e32 v44, v0
	v_mov_b32_e32 v45, v0
	v_mov_b32_e32 v46, v0
	v_mov_b32_e32 v47, v0
	v_mov_b32_e32 v56, v0
	v_mov_b32_e32 v57, v0
	v_mov_b32_e32 v58, v0
	v_mov_b32_e32 v59, v0
	v_mov_b32_e32 v60, v0
	v_mov_b32_e32 v61, v0
	v_mov_b32_e32 v62, v0
	v_mov_b32_e32 v63, v0
	v_mov_b32_e32 v64, v0
	v_mov_b32_e32 v65, v0
	s_waitcnt vmcnt(15)
	v_mov_b32_e32 v66, v0
	v_mov_b32_e32 v67, v0
	v_mov_b32_e32 v68, v0
	v_mov_b32_e32 v69, v0
	v_mov_b32_e32 v70, v0
	v_mov_b32_e32 v71, v0
	v_mov_b32_e32 v80, v0
	v_mov_b32_e32 v81, v0
	v_mov_b32_e32 v82, v0
	v_mov_b32_e32 v83, v0
	v_mov_b32_e32 v84, v0
	v_mov_b32_e32 v85, v0
	v_mov_b32_e32 v86, v0
	v_mov_b32_e32 v87, v0
	v_mov_b32_e32 v96, v0
	v_mov_b32_e32 v97, v0
	v_mov_b32_e32 v98, v0
	v_mov_b32_e32 v99, v0
	v_mov_b32_e32 v100, v0
	v_mov_b32_e32 v101, v0
	v_mov_b32_e32 v102, v0
	v_mov_b32_e32 v103, v0
	v_mov_b32_e32 v112, v0
	v_mov_b32_e32 v113, v0
	v_mov_b32_e32 v114, v0
	v_mov_b32_e32 v115, v0
	v_mov_b32_e32 v116, v0
	v_mov_b32_e32 v117, v0
	v_mov_b32_e32 v118, v0
	v_mov_b32_e32 v119, v0
	v_mov_b32_e32 v72, v0
	v_mov_b32_e32 v73, v0
	v_mov_b32_e32 v74, v0
	v_mov_b32_e32 v75, v0
	v_mov_b32_e32 v76, v0
	v_mov_b32_e32 v77, v0
	v_mov_b32_e32 v78, v0
	v_mov_b32_e32 v79, v0
	v_mov_b32_e32 v88, v0
	v_mov_b32_e32 v89, v0
	v_mov_b32_e32 v90, v0
	v_mov_b32_e32 v91, v0
	v_mov_b32_e32 v92, v0
	v_mov_b32_e32 v93, v0
	v_mov_b32_e32 v94, v0
	v_mov_b32_e32 v95, v0
	v_mov_b32_e32 v104, v0
	v_mov_b32_e32 v105, v0
	v_mov_b32_e32 v106, v0
	v_mov_b32_e32 v107, v0
	v_mov_b32_e32 v108, v0
	v_mov_b32_e32 v109, v0
	v_mov_b32_e32 v110, v0
	v_mov_b32_e32 v111, v0
	v_mov_b32_e32 v120, v0
	v_mov_b32_e32 v121, v0
	v_mov_b32_e32 v122, v0
	v_mov_b32_e32 v123, v0
	v_mov_b32_e32 v124, v0
	v_mov_b32_e32 v125, v0
	v_mov_b32_e32 v126, v0
	v_mov_b32_e32 v127, v0
	v_readlane_b32 vcc_lo, v246, 6
	s_nop 1
	s_cmp_lt_u32 vcc_lo, 4
	s_cbranch_scc0 .Lprio_1943
	s_setprio 1

; template <class Epi, class Sched, bool ALIGN_EPI = false, bool SP2 = false>
; __device__ __forceinline__ void gemm_phase(PG8_LAS unsigned char* lds, const Gemm g, const Sched& S, const Epi& E, const int wid  ) {
;     ...
;         const unsigned nA = has_next ? (unsigned)g.asel(nxt.pn) * (unsigned)g.a_stride + (unsigned)nxt.pm * tstep : cA, nB = has_next ? (unsigned)nxt.pn * tstep : cB;
;         for (int t = 0; t < nt; t += 2) {
;             const bool last = (t == nt - 2);
;             const unsigned a1 = cA + (unsigned)(t + 1) * kstep;
;             const unsigned a2 = last ? nA : cA + (unsigned)(t + 2) * kstep, b2 = last ? nB : cB + (unsigned)(t + 2) * kstep;
;             const unsigned a3 = a2 + kstep, b3 = b2 + kstep;
;     ...
; #pragma unroll
;         for (int a = 0; a < 2; ++a)
; #pragma unroll
;             for (int b = 0; b < 2; ++b)
; #pragma unroll
;                 for (int m = 0; m < 4; ++m)
; #pragma unroll
;                     for (int n = 0; n < 2; ++n) acc[a][b][m][n] = (f32x4){0.f, 0.f, 0.f, 0.f};
;         cur = nxt; cA = nA; cB = nB; ++ui;
.LBB0_2036:
	s_lshl_b32 s90, s89, 20
	s_and_b64 s[6:7], s[4:5], exec
	s_cselect_b32 s6, s90, s48
	s_lshl_b32 s91, s88, 20
	s_and_b64 s[18:19], s[4:5], exec
	v_mov_b32_e32 v56, 0
	s_cselect_b32 s7, s91, s9
	s_add_i32 s8, s48, 0x80080
	s_addk_i32 s9, 0x100
	s_mov_b32 s48, -2
	v_mov_b32_e32 v57, v56
	v_mov_b32_e32 v58, v56
	v_mov_b32_e32 v59, v56
	v_mov_b32_e32 v60, v56
	v_mov_b32_e32 v61, v56
	v_mov_b32_e32 v62, v56
	v_mov_b32_e32 v63, v56
	v_mov_b32_e32 v64, v56
	v_mov_b32_e32 v65, v56
	v_mov_b32_e32 v66, v56
	v_mov_b32_e32 v67, v56
	v_mov_b32_e32 v68, v56
	v_mov_b32_e32 v69, v56
	v_mov_b32_e32 v70, v56
	v_mov_b32_e32 v71, v56
	v_mov_b32_e32 v72, v56
	v_mov_b32_e32 v73, v56
	v_mov_b32_e32 v74, v56
	v_mov_b32_e32 v75, v56
	v_mov_b32_e32 v80, v56
	v_mov_b32_e32 v81, v56
	v_mov_b32_e32 v82, v56
	v_mov_b32_e32 v83, v56
	v_mov_b32_e32 v0, v56
	v_mov_b32_e32 v1, v56
	s_waitcnt lgkmcnt(7)
	v_mov_b32_e32 v2, v56
	v_mov_b32_e32 v3, v56
	s_waitcnt lgkmcnt(6)
	v_mov_b32_e32 v4, v56
	v_mov_b32_e32 v5, v56
	s_waitcnt lgkmcnt(5)
	v_mov_b32_e32 v6, v56
	v_mov_b32_e32 v7, v56
	v_mov_b32_e32 v48, v56
	v_mov_b32_e32 v49, v56
	v_mov_b32_e32 v50, v56
	v_mov_b32_e32 v51, v56
	v_mov_b32_e32 v92, v56
	v_mov_b32_e32 v93, v56
	v_mov_b32_e32 v94, v56
	v_mov_b32_e32 v95, v56
	v_mov_b32_e32 v76, v56
	v_mov_b32_e32 v77, v56
	v_mov_b32_e32 v78, v56
	v_mov_b32_e32 v79, v56
	v_mov_b32_e32 v84, v56
	v_mov_b32_e32 v85, v56
	v_mov_b32_e32 v86, v56
	v_mov_b32_e32 v87, v56
	v_mov_b32_e32 v88, v56
	v_mov_b32_e32 v89, v56
	v_mov_b32_e32 v90, v56
	v_mov_b32_e32 v91, v56
	v_mov_b32_e32 v96, v56
	v_mov_b32_e32 v97, v56
	v_mov_b32_e32 v98, v56
	v_mov_b32_e32 v99, v56
	v_mov_b32_e32 v100, v56
	v_mov_b32_e32 v101, v56
	v_mov_b32_e32 v102, v56
	v_mov_b32_e32 v103, v56
	v_mov_b32_e32 v104, v56
	v_mov_b32_e32 v105, v56
	v_mov_b32_e32 v106, v56
	v_mov_b32_e32 v107, v56
	v_mov_b32_e32 v108, v56
	v_mov_b32_e32 v109, v56
	v_mov_b32_e32 v110, v56
	v_mov_b32_e32 v111, v56
	v_mov_b32_e32 v112, v56
	v_mov_b32_e32 v113, v56
	v_mov_b32_e32 v114, v56
	v_mov_b32_e32 v115, v56
	v_mov_b32_e32 v116, v56
	v_mov_b32_e32 v117, v56
	v_mov_b32_e32 v118, v56
	v_mov_b32_e32 v119, v56
	v_mov_b32_e32 v124, v56
	v_mov_b32_e32 v125, v56
	v_mov_b32_e32 v126, v56
	v_mov_b32_e32 v127, v56
	v_mov_b32_e32 v128, v56
	v_mov_b32_e32 v129, v56
	v_mov_b32_e32 v130, v56
	v_mov_b32_e32 v131, v56
	v_mov_b32_e32 v136, v56
	v_mov_b32_e32 v137, v56
	v_mov_b32_e32 v138, v56
	v_mov_b32_e32 v139, v56
	s_waitcnt lgkmcnt(4)
	v_mov_b32_e32 v8, v56
	v_mov_b32_e32 v9, v56
	s_waitcnt lgkmcnt(3)
	v_mov_b32_e32 v10, v56
	v_mov_b32_e32 v11, v56
	s_waitcnt lgkmcnt(2)
	v_mov_b32_e32 v12, v56
	v_mov_b32_e32 v13, v56
	s_waitcnt lgkmcnt(1)
	v_mov_b32_e32 v14, v56
	v_mov_b32_e32 v15, v56
	v_mov_b32_e32 v120, v56
	v_mov_b32_e32 v121, v56
	v_mov_b32_e32 v122, v56
	v_mov_b32_e32 v123, v56
	v_mov_b32_e32 v156, v56
	v_mov_b32_e32 v157, v56
	v_mov_b32_e32 v158, v56
	v_mov_b32_e32 v159, v56
	v_mov_b32_e32 v132, v56
	v_mov_b32_e32 v133, v56
	v_mov_b32_e32 v134, v56
	v_mov_b32_e32 v135, v56
	v_mov_b32_e32 v140, v56
	v_mov_b32_e32 v141, v56
	v_mov_b32_e32 v142, v56
	v_mov_b32_e32 v143, v56
	v_mov_b32_e32 v144, v56
	v_mov_b32_e32 v145, v56
	v_mov_b32_e32 v146, v56
	v_mov_b32_e32 v147, v56
	v_mov_b32_e32 v148, v56
	v_mov_b32_e32 v149, v56
	v_mov_b32_e32 v150, v56
	v_mov_b32_e32 v151, v56
	v_mov_b32_e32 v52, v56
	v_mov_b32_e32 v53, v56
	v_mov_b32_e32 v54, v56
	v_mov_b32_e32 v55, v56
	v_mov_b32_e32 v152, v56
	v_mov_b32_e32 v153, v56
	v_mov_b32_e32 v154, v56
	v_mov_b32_e32 v155, v56
	v_readlane_b32 vcc_lo, v246, 6
	s_nop 1
	s_cmp_lt_u32 vcc_lo, 4
	s_cbranch_scc0 .Lprio_2037
	s_setprio 1

; template <class Epi, class Sched, bool ALIGN_EPI = false, bool SP2 = false>
; __device__ __forceinline__ void gemm_phase(PG8_LAS unsigned char* lds, const Gemm g, const Sched& S, const Epi& E, const int wid  ) {
;     ...
;         const unsigned nA = has_next ? (unsigned)g.asel(nxt.pn) * (unsigned)g.a_stride + (unsigned)nxt.pm * tstep : cA, nB = has_next ? (unsigned)nxt.pn * tstep : cB;
;         for (int t = 0; t < nt; t += 2) {
;             const bool last = (t == nt - 2);
;             const unsigned a1 = cA + (unsigned)(t + 1) * kstep;
;             const unsigned a2 = last ? nA : cA + (unsigned)(t + 2) * kstep, b2 = last ? nB : cB + (unsigned)(t + 2) * kstep;
;             const unsigned a3 = a2 + kstep, b3 = b2 + kstep;
;     ...
; #pragma unroll
;         for (int a = 0; a < 2; ++a)
; #pragma unroll
;             for (int b = 0; b < 2; ++b)
; #pragma unroll
;                 for (int m = 0; m < 4; ++m)
; #pragma unroll
;                     for (int n = 0; n < 2; ++n) acc[a][b][m][n] = (f32x4){0.f, 0.f, 0.f, 0.f};
;         cur = nxt; cA = nA; cB = nB; ++ui;
.LBB0_2379:
	s_mul_i32 s50, s49, 0x2c0000
	s_and_b64 s[0:1], s[4:5], exec
	s_mul_i32 s51, s48, 0x2c0000
	v_mov_b32_e32 v0, 0
	s_cselect_b32 s0, s50, s16
	s_cselect_b32 s1, s51, s55
	s_add_i32 s16, s16, 0x160080
	s_addk_i32 s55, 0x100
	s_mov_b32 s58, -2
	s_waitcnt lgkmcnt(0)
	v_mov_b32_e32 v1, v0
	v_mov_b32_e32 v2, v0
	v_mov_b32_e32 v3, v0
	v_mov_b32_e32 v4, v0
	v_mov_b32_e32 v5, v0
	v_mov_b32_e32 v6, v0
	v_mov_b32_e32 v7, v0
	v_mov_b32_e32 v16, v0
	v_mov_b32_e32 v17, v0
	v_mov_b32_e32 v18, v0
	v_mov_b32_e32 v19, v0
	v_mov_b32_e32 v20, v0
	v_mov_b32_e32 v21, v0
	v_mov_b32_e32 v22, v0
	v_mov_b32_e32 v23, v0
	v_mov_b32_e32 v32, v0
	v_mov_b32_e32 v33, v0
	v_mov_b32_e32 v34, v0
	v_mov_b32_e32 v35, v0
	v_mov_b32_e32 v36, v0
	v_mov_b32_e32 v37, v0
	v_mov_b32_e32 v38, v0
	v_mov_b32_e32 v39, v0
	v_mov_b32_e32 v48, v0
	v_mov_b32_e32 v49, v0
	v_mov_b32_e32 v50, v0
	v_mov_b32_e32 v51, v0
	v_mov_b32_e32 v52, v0
	v_mov_b32_e32 v53, v0
	v_mov_b32_e32 v54, v0
	v_mov_b32_e32 v55, v0
	v_mov_b32_e32 v8, v0
	v_mov_b32_e32 v9, v0
	v_mov_b32_e32 v10, v0
	v_mov_b32_e32 v11, v0
	v_mov_b32_e32 v12, v0
	v_mov_b32_e32 v13, v0
	v_mov_b32_e32 v14, v0
	v_mov_b32_e32 v15, v0
	v_mov_b32_e32 v24, v0
	v_mov_b32_e32 v25, v0
	v_mov_b32_e32 v26, v0
	v_mov_b32_e32 v27, v0
	v_mov_b32_e32 v28, v0
	v_mov_b32_e32 v29, v0
	v_mov_b32_e32 v30, v0
	v_mov_b32_e32 v31, v0
	v_mov_b32_e32 v40, v0
	v_mov_b32_e32 v41, v0
	v_mov_b32_e32 v42, v0
	v_mov_b32_e32 v43, v0
	v_mov_b32_e32 v44, v0
	v_mov_b32_e32 v45, v0
	v_mov_b32_e32 v46, v0
	v_mov_b32_e32 v47, v0
	v_mov_b32_e32 v56, v0
	v_mov_b32_e32 v57, v0
	v_mov_b32_e32 v58, v0
	v_mov_b32_e32 v59, v0
	v_mov_b32_e32 v60, v0
	v_mov_b32_e32 v61, v0
	v_mov_b32_e32 v62, v0
	v_mov_b32_e32 v63, v0
	v_mov_b32_e32 v64, v0
	v_mov_b32_e32 v65, v0
	s_waitcnt vmcnt(15)
	v_mov_b32_e32 v66, v0
	v_mov_b32_e32 v67, v0
	v_mov_b32_e32 v68, v0
	v_mov_b32_e32 v69, v0
	v_mov_b32_e32 v70, v0
	v_mov_b32_e32 v71, v0
	v_mov_b32_e32 v80, v0
	v_mov_b32_e32 v81, v0
	v_mov_b32_e32 v82, v0
	v_mov_b32_e32 v83, v0
	v_mov_b32_e32 v84, v0
	v_mov_b32_e32 v85, v0
	v_mov_b32_e32 v86, v0
	v_mov_b32_e32 v87, v0
	v_mov_b32_e32 v96, v0
	v_mov_b32_e32 v97, v0
	v_mov_b32_e32 v98, v0
	v_mov_b32_e32 v99, v0
	v_mov_b32_e32 v100, v0
	v_mov_b32_e32 v101, v0
	v_mov_b32_e32 v102, v0
	v_mov_b32_e32 v103, v0
	v_mov_b32_e32 v112, v0
	v_mov_b32_e32 v113, v0
	v_mov_b32_e32 v114, v0
	v_mov_b32_e32 v115, v0
	v_mov_b32_e32 v116, v0
	v_mov_b32_e32 v117, v0
	v_mov_b32_e32 v118, v0
	v_mov_b32_e32 v119, v0
	v_mov_b32_e32 v72, v0
	v_mov_b32_e32 v73, v0
	v_mov_b32_e32 v74, v0
	v_mov_b32_e32 v75, v0
	v_mov_b32_e32 v76, v0
	v_mov_b32_e32 v77, v0
	v_mov_b32_e32 v78, v0
	v_mov_b32_e32 v79, v0
	v_mov_b32_e32 v88, v0
	v_mov_b32_e32 v89, v0
	v_mov_b32_e32 v90, v0
	v_mov_b32_e32 v91, v0
	v_mov_b32_e32 v92, v0
	v_mov_b32_e32 v93, v0
	v_mov_b32_e32 v94, v0
	v_mov_b32_e32 v95, v0
	v_mov_b32_e32 v104, v0
	v_mov_b32_e32 v105, v0
	v_mov_b32_e32 v106, v0
	v_mov_b32_e32 v107, v0
	v_mov_b32_e32 v108, v0
	v_mov_b32_e32 v109, v0
	v_mov_b32_e32 v110, v0
	v_mov_b32_e32 v111, v0
	v_mov_b32_e32 v120, v0
	v_mov_b32_e32 v121, v0
	v_mov_b32_e32 v122, v0
	v_mov_b32_e32 v123, v0
	v_mov_b32_e32 v124, v0
	v_mov_b32_e32 v125, v0
	v_mov_b32_e32 v126, v0
	v_mov_b32_e32 v127, v0
	v_readlane_b32 vcc_lo, v246, 6
	s_nop 1
	s_cmp_lt_u32 vcc_lo, 4
	s_cbranch_scc0 .Lprio_2380
	s_setprio 1

; template <class Epi, class Sched, bool ALIGN_EPI = false, bool SP2 = false>
; __device__ __forceinline__ void gemm_phase(PG8_LAS unsigned char* lds, const Gemm g, const Sched& S, const Epi& E, const int wid  ) {
;     ...
;         const unsigned nA = has_next ? (unsigned)g.asel(nxt.pn) * (unsigned)g.a_stride + (unsigned)nxt.pm * tstep : cA, nB = has_next ? (unsigned)nxt.pn * tstep : cB;
;         for (int t = 0; t < nt; t += 2) {
;             const bool last = (t == nt - 2);
;             const unsigned a1 = cA + (unsigned)(t + 1) * kstep;
;             const unsigned a2 = last ? nA : cA + (unsigned)(t + 2) * kstep, b2 = last ? nB : cB + (unsigned)(t + 2) * kstep;
;             const unsigned a3 = a2 + kstep, b3 = b2 + kstep;
;     ...
; #pragma unroll
;         for (int a = 0; a < 2; ++a)
; #pragma unroll
;             for (int b = 0; b < 2; ++b)
; #pragma unroll
;                 for (int m = 0; m < 4; ++m)
; #pragma unroll
;                     for (int n = 0; n < 2; ++n) acc[a][b][m][n] = (f32x4){0.f, 0.f, 0.f, 0.f};
;         cur = nxt; cA = nA; cB = nB; ++ui;
.LBB0_4015:
	s_lshl_b32 s70, s69, 20
	s_and_b64 s[14:15], s[4:5], exec
	s_cselect_b32 s33, s70, s41
	s_lshl_b32 s71, s68, 20
	s_and_b64 s[14:15], s[4:5], exec
	v_mov_b32_e32 v0, 0
	s_cselect_b32 s40, s71, s73
	s_add_i32 s41, s41, 0x80080
	s_add_i32 s72, s73, 0x100
	s_mov_b32 s73, -2
	s_waitcnt lgkmcnt(0)
	v_mov_b32_e32 v1, v0
	v_mov_b32_e32 v2, v0
	v_mov_b32_e32 v3, v0
	v_mov_b32_e32 v4, v0
	v_mov_b32_e32 v5, v0
	s_waitcnt lgkmcnt(6)
	v_mov_b32_e32 v6, v0
	v_mov_b32_e32 v7, v0
	s_waitcnt lgkmcnt(1)
	v_mov_b32_e32 v16, v0
	v_mov_b32_e32 v17, v0
	s_waitcnt lgkmcnt(0)
	v_mov_b32_e32 v18, v0
	v_mov_b32_e32 v19, v0
	v_mov_b32_e32 v20, v0
	v_mov_b32_e32 v21, v0
	v_mov_b32_e32 v22, v0
	v_mov_b32_e32 v23, v0
	v_mov_b32_e32 v32, v0
	v_mov_b32_e32 v33, v0
	v_mov_b32_e32 v34, v0
	v_mov_b32_e32 v35, v0
	v_mov_b32_e32 v36, v0
	v_mov_b32_e32 v37, v0
	v_mov_b32_e32 v38, v0
	v_mov_b32_e32 v39, v0
	v_mov_b32_e32 v48, v0
	v_mov_b32_e32 v49, v0
	v_mov_b32_e32 v50, v0
	v_mov_b32_e32 v51, v0
	v_mov_b32_e32 v52, v0
	v_mov_b32_e32 v53, v0
	v_mov_b32_e32 v54, v0
	v_mov_b32_e32 v55, v0
	v_mov_b32_e32 v8, v0
	v_mov_b32_e32 v9, v0
	v_mov_b32_e32 v10, v0
	v_mov_b32_e32 v11, v0
	v_mov_b32_e32 v12, v0
	v_mov_b32_e32 v13, v0
	v_mov_b32_e32 v14, v0
	v_mov_b32_e32 v15, v0
	v_mov_b32_e32 v24, v0
	v_mov_b32_e32 v25, v0
	v_mov_b32_e32 v26, v0
	v_mov_b32_e32 v27, v0
	v_mov_b32_e32 v28, v0
	v_mov_b32_e32 v29, v0
	v_mov_b32_e32 v30, v0
	v_mov_b32_e32 v31, v0
	v_mov_b32_e32 v40, v0
	v_mov_b32_e32 v41, v0
	v_mov_b32_e32 v42, v0
	v_mov_b32_e32 v43, v0
	v_mov_b32_e32 v44, v0
	v_mov_b32_e32 v45, v0
	v_mov_b32_e32 v46, v0
	v_mov_b32_e32 v47, v0
	v_mov_b32_e32 v56, v0
	v_mov_b32_e32 v57, v0
	v_mov_b32_e32 v58, v0
	v_mov_b32_e32 v59, v0
	v_mov_b32_e32 v60, v0
	v_mov_b32_e32 v61, v0
	v_mov_b32_e32 v62, v0
	v_mov_b32_e32 v63, v0
	v_mov_b32_e32 v64, v0
	v_mov_b32_e32 v65, v0
	v_mov_b32_e32 v66, v0
	v_mov_b32_e32 v67, v0
	v_mov_b32_e32 v68, v0
	v_mov_b32_e32 v69, v0
	v_mov_b32_e32 v70, v0
	v_mov_b32_e32 v71, v0
	v_mov_b32_e32 v80, v0
	v_mov_b32_e32 v81, v0
	v_mov_b32_e32 v82, v0
	v_mov_b32_e32 v83, v0
	v_mov_b32_e32 v84, v0
	v_mov_b32_e32 v85, v0
	v_mov_b32_e32 v86, v0
	v_mov_b32_e32 v87, v0
	v_mov_b32_e32 v96, v0
	v_mov_b32_e32 v97, v0
	v_mov_b32_e32 v98, v0
	v_mov_b32_e32 v99, v0
	v_mov_b32_e32 v100, v0
	v_mov_b32_e32 v101, v0
	v_mov_b32_e32 v102, v0
	v_mov_b32_e32 v103, v0
	v_mov_b32_e32 v112, v0
	v_mov_b32_e32 v113, v0
	v_mov_b32_e32 v114, v0
	v_mov_b32_e32 v115, v0
	v_mov_b32_e32 v116, v0
	v_mov_b32_e32 v117, v0
	v_mov_b32_e32 v118, v0
	v_mov_b32_e32 v119, v0
	v_mov_b32_e32 v72, v0
	v_mov_b32_e32 v73, v0
	v_mov_b32_e32 v74, v0
	v_mov_b32_e32 v75, v0
	v_mov_b32_e32 v76, v0
	v_mov_b32_e32 v77, v0
	v_mov_b32_e32 v78, v0
	v_mov_b32_e32 v79, v0
	v_mov_b32_e32 v88, v0
	v_mov_b32_e32 v89, v0
	v_mov_b32_e32 v90, v0
	v_mov_b32_e32 v91, v0
	v_mov_b32_e32 v92, v0
	v_mov_b32_e32 v93, v0
	v_mov_b32_e32 v94, v0
	v_mov_b32_e32 v95, v0
	v_mov_b32_e32 v104, v0
	v_mov_b32_e32 v105, v0
	v_mov_b32_e32 v106, v0
	v_mov_b32_e32 v107, v0
	v_mov_b32_e32 v108, v0
	v_mov_b32_e32 v109, v0
	v_mov_b32_e32 v110, v0
	v_mov_b32_e32 v111, v0
	v_mov_b32_e32 v120, v0
	v_mov_b32_e32 v121, v0
	v_mov_b32_e32 v122, v0
	v_mov_b32_e32 v123, v0
	v_mov_b32_e32 v124, v0
	v_mov_b32_e32 v125, v0
	v_mov_b32_e32 v126, v0
	v_mov_b32_e32 v127, v0
	v_readlane_b32 vcc_lo, v246, 6
	s_nop 1
	s_cmp_lt_u32 vcc_lo, 4
	s_cbranch_scc0 .Lprio_4016
	s_setprio 1
